# MLA fast path: direct fast-to-fast loop back edge, V fragment reads rebalanced with exact lgkmcnt waits
# speedup vs baseline: 1.0619x; 1.0076x over previous
.Lmla_fast_nodma:
	s_waitcnt lgkmcnt(0)
	v_mfma_f32_32x32x16_bf16 v[50:65], v[194:197], v[74:77], v[234:249]
	ds_read_b128 v[194:197], v0 offset:6656
	v_add_f32_e32 v254, v202, v203
	v_add_f32_e32 v255, v204, v205
	v_add_f32_e32 v254, v254, v206
	v_add_f32_e32 v255, v255, v207
	v_add_f32_e32 v254, v254, v208
	v_add_f32_e32 v255, v255, v209
	v_mfma_f32_32x32x16_bf16 v[50:65], v[150:153], v[78:81], v[50:65]
	ds_read_b128 v[150:153], v0 offset:6688
	v_add_f32_e32 v254, v254, v210
	v_add_f32_e32 v255, v255, v211
	v_add_f32_e32 v254, v254, v212
	v_add_f32_e32 v255, v255, v213
	v_add_f32_e32 v254, v254, v214
	v_add_f32_e32 v255, v255, v215
	v_mfma_f32_32x32x16_bf16 v[50:65], v[158:161], v[82:85], v[50:65]
	ds_read_b128 v[158:161], v0 offset:6720
	v_add_f32_e32 v254, v254, v216
	v_add_f32_e32 v255, v255, v217
	v_add_f32_e32 v254, v254, v218
	v_add_f32_e32 v255, v255, v219
	v_add_f32_e32 v254, v254, v220
	v_mfma_f32_32x32x16_bf16 v[50:65], v[162:165], v[86:89], v[50:65]
	ds_read_b128 v[162:165], v0 offset:6752
	v_add_f32_e32 v255, v255, v221
	v_add_f32_e32 v254, v254, v222
	v_add_f32_e32 v255, v255, v223
	v_add_f32_e32 v254, v254, v224
	v_add_f32_e32 v255, v255, v225
	v_mfma_f32_32x32x16_bf16 v[50:65], v[174:177], v[90:93], v[50:65]
	ds_read_b128 v[174:177], v0 offset:6784
	v_add_f32_e32 v254, v254, v226
	v_add_f32_e32 v255, v255, v227
	v_add_f32_e32 v254, v254, v228
	v_add_f32_e32 v255, v255, v229
	v_add_f32_e32 v254, v254, v230
	v_mfma_f32_32x32x16_bf16 v[50:65], v[178:181], v[94:97], v[50:65]
	ds_read_b128 v[178:181], v0 offset:6816
	v_add_f32_e32 v255, v255, v231
	v_add_f32_e32 v254, v254, v232
	v_add_f32_e32 v255, v255, v233
	v_add_f32_e32 v254, v254, v255
	v_add_f32_e32 v147, v147, v254
	s_waitcnt lgkmcnt(5)
	v_mfma_f32_32x32x16_bf16 v[34:49], v[194:197], v[74:77], v[234:249]
	ds_read_b64_tr_b16 v[126:127], v142 offset:13312
	ds_read_b64_tr_b16 v[128:129], v142 offset:14848
	ds_read_b64_tr_b16 v[124:125], v142 offset:14912
	ds_read_b64_tr_b16 v[122:123], v142 offset:13376
	s_waitcnt lgkmcnt(8)
	v_mfma_f32_32x32x16_bf16 v[34:49], v[150:153], v[78:81], v[34:49]
	ds_read_b64_tr_b16 v[118:119], v142 offset:16384
	ds_read_b64_tr_b16 v[120:121], v142 offset:17920
	ds_read_b64_tr_b16 v[116:117], v142 offset:17984
	ds_read_b64_tr_b16 v[114:115], v142 offset:16448
	s_waitcnt lgkmcnt(11)
	v_mfma_f32_32x32x16_bf16 v[34:49], v[158:161], v[82:85], v[34:49]
	ds_read_b64_tr_b16 v[110:111], v142 offset:19456
	ds_read_b64_tr_b16 v[112:113], v142 offset:20992
	ds_read_b64_tr_b16 v[108:109], v142 offset:21056
	ds_read_b64_tr_b16 v[106:107], v142 offset:19520
	v_max3_f32 v0, v50, v51, v52
	v_max3_f32 v0, v0, v53, v54
	s_waitcnt lgkmcnt(11)
	v_mfma_f32_32x32x16_bf16 v[34:49], v[162:165], v[86:89], v[34:49]
	ds_read_b64_tr_b16 v[102:103], v142 offset:22528
	ds_read_b64_tr_b16 v[104:105], v142 offset:24064
	ds_read_b64_tr_b16 v[100:101], v142 offset:24128
	ds_read_b64_tr_b16 v[98:99], v142 offset:22592
	v_max3_f32 v0, v0, v55, v56
	v_max3_f32 v0, v0, v57, v58
	v_mfma_f32_32x32x16_bf16 v[34:49], v[174:177], v[90:93], v[34:49]
	v_max3_f32 v0, v0, v59, v60
	v_max3_f32 v0, v0, v61, v62
	v_max3_f32 v0, v0, v63, v64
	v_max3_f32 v0, v0, v65, v65
	v_exp_f32_e32 v202, v50
	v_mfma_f32_32x32x16_bf16 v[34:49], v[178:181], v[94:97], v[34:49]
	s_and_b64 vcc, exec, s[16:17]
	s_cbranch_vccz .Lmla_fast_nostag
	s_waitcnt vmcnt(0) lgkmcnt(0)
	s_barrier
	s_mov_b64 s[16:17], 0
.Lmla_fast_nostag:
	v_exp_f32_e32 v203, v51
	v_exp_f32_e32 v204, v52
	v_exp_f32_e32 v205, v53
	v_exp_f32_e32 v206, v54
	v_exp_f32_e32 v207, v55
	v_exp_f32_e32 v208, v56
	v_exp_f32_e32 v209, v57
	v_exp_f32_e32 v210, v58
	v_exp_f32_e32 v211, v59
	v_exp_f32_e32 v212, v60
	v_max3_f32 v149, v34, v35, v36
	v_exp_f32_e32 v213, v61
	v_max3_f32 v149, v149, v37, v38
	v_exp_f32_e32 v214, v62
	v_max3_f32 v149, v149, v39, v40
	v_exp_f32_e32 v215, v63
	v_max3_f32 v149, v149, v41, v42
	v_exp_f32_e32 v216, v64
	v_max3_f32 v149, v149, v43, v44
	v_exp_f32_e32 v217, v65
	v_max3_f32 v149, v149, v45, v46
	v_max3_f32 v149, v149, v47, v48
	v_max3_f32 v149, v149, v49, v49
	v_max_f32_e32 v149, v149, v149
	v_max_f32_e32 v0, v0, v0
	v_max_f32_e32 v0, v0, v149
	v_cmp_lt_f32_e32 vcc, s21, v0
	s_cbranch_vccnz .Lmla_fast_rescale
.Lmla_fast_ok:
	v_cvt_pk_bf16_f32 v166, v202, v203
	v_cvt_pk_bf16_f32 v167, v204, v205
	v_cvt_pk_bf16_f32 v168, v206, v207
	v_cvt_pk_bf16_f32 v169, v208, v209
	s_waitcnt lgkmcnt(0)
	s_add_i32 s34, s31, 64
	s_cmp_le_u32 s34, s4
	s_cselect_b32 s42, 1, 0
	s_add_i32 s8, s30, 1
	s_and_b32 s8, s8, 3
	s_mulk_i32 s8, 0x6400
	v_add3_u32 v0, s8, v143, v132
	v_mfma_f32_32x32x16_bf16 v[18:33], v[126:129], v[166:169], v[18:33]
	v_exp_f32_e32 v218, v34
	v_cvt_pk_bf16_f32 v170, v210, v211
	v_cvt_pk_bf16_f32 v171, v212, v213
	v_cvt_pk_bf16_f32 v172, v214, v215
	v_cvt_pk_bf16_f32 v173, v216, v217
	v_mfma_f32_32x32x16_bf16 v[2:17], v[122:125], v[166:169], v[2:17]
	v_exp_f32_e32 v219, v35
	v_exp_f32_e32 v220, v36
	v_exp_f32_e32 v221, v37
	v_mfma_f32_32x32x16_bf16 v[18:33], v[118:121], v[170:173], v[18:33]
	v_exp_f32_e32 v222, v38
	v_exp_f32_e32 v223, v39
	ds_read_b128 v[194:197], v0
	ds_read_b128 v[150:153], v0 offset:32
	v_mfma_f32_32x32x16_bf16 v[2:17], v[114:117], v[170:173], v[2:17]
	v_exp_f32_e32 v224, v40
	v_exp_f32_e32 v225, v41
	v_cvt_pk_bf16_f32 v166, v218, v219
	v_cvt_pk_bf16_f32 v167, v220, v221
	v_cvt_pk_bf16_f32 v168, v222, v223
	v_cvt_pk_bf16_f32 v169, v224, v225
	ds_read_b128 v[158:161], v0 offset:64
	ds_read_b128 v[162:165], v0 offset:96
	v_mfma_f32_32x32x16_bf16 v[18:33], v[110:113], v[166:169], v[18:33]
	v_exp_f32_e32 v226, v42
	v_exp_f32_e32 v227, v43
	v_exp_f32_e32 v228, v44
	v_mfma_f32_32x32x16_bf16 v[2:17], v[106:109], v[166:169], v[2:17]
	v_exp_f32_e32 v229, v45
	v_exp_f32_e32 v230, v46
	v_exp_f32_e32 v231, v47
	v_exp_f32_e32 v232, v48
	v_exp_f32_e32 v233, v49
	ds_read_b128 v[174:177], v0 offset:128
	ds_read_b128 v[178:181], v0 offset:160
	v_cvt_pk_bf16_f32 v170, v226, v227
	v_cvt_pk_bf16_f32 v171, v228, v229
	v_cvt_pk_bf16_f32 v172, v230, v231
	v_cvt_pk_bf16_f32 v173, v232, v233
	s_nop 1
	v_mfma_f32_32x32x16_bf16 v[18:33], v[102:105], v[170:173], v[18:33]
	v_mfma_f32_32x32x16_bf16 v[2:17], v[98:101], v[170:173], v[2:17]
	s_add_i32 s30, s30, 1
	s_add_i32 s31, s31, 64
	v_subrev_u32_e32 v146, 64, v146
	s_cmp_lg_u32 s42, 0
	s_cbranch_scc0 .Lmla_fast_generic
	s_not_b64 s[38:39], s[38:39]
	s_not_b64 s[16:17], s[38:39]
	s_branch .Lmla_fast
.Lmla_fast_generic:
	s_cmp_lg_u32 s20, s30
	s_cbranch_scc1 .LBB0_478
	s_branch .LBB0_430
